# output rows stored write-through (sc1) from the fused final epilogue so that little dirty data is left for the end-of-kernel flush
# baseline (speedup 1.0000x reference)
.Lfz_synced:
	s_mov_b64 exec, s[20:21]
	s_barrier
	v_mul_u32_u24_e32 v154, 0x4800, v129
	v_add_u32_e32 v154, v154, v152
	v_lshlrev_b32_e32 v154, 2, v154
	v_add_u32_e32 v155, 0x9000, v154
	global_load_dword v180, v154, s[100:101] offset:0 sc1
	global_load_dword v181, v155, s[100:101] offset:0 sc1
	global_load_dword v182, v154, s[100:101] offset:64 sc1
	global_load_dword v183, v155, s[100:101] offset:64 sc1
	global_load_dword v184, v154, s[100:101] offset:128 sc1
	global_load_dword v185, v155, s[100:101] offset:128 sc1
	global_load_dword v186, v154, s[100:101] offset:192 sc1
	global_load_dword v187, v155, s[100:101] offset:192 sc1
	global_load_dword v188, v154, s[100:101] offset:512 sc1
	global_load_dword v189, v155, s[100:101] offset:512 sc1
	global_load_dword v190, v154, s[100:101] offset:576 sc1
	global_load_dword v191, v155, s[100:101] offset:576 sc1
	global_load_dword v192, v154, s[100:101] offset:640 sc1
	global_load_dword v193, v155, s[100:101] offset:640 sc1
	global_load_dword v194, v154, s[100:101] offset:704 sc1
	global_load_dword v195, v155, s[100:101] offset:704 sc1
	s_waitcnt vmcnt(0)
	v_add_f32_e32 v160, v180, v181
	v_add_f32_e32 v161, v182, v183
	v_add_f32_e32 v162, v184, v185
	v_add_f32_e32 v163, v186, v187
	v_add_f32_e32 v164, v188, v189
	v_add_f32_e32 v165, v190, v191
	v_add_f32_e32 v166, v192, v193
	v_add_f32_e32 v167, v194, v195
	v_mov_b32_e32 v168, v160
	v_mov_b32_e32 v169, v161
	v_mov_b32_e32 v170, v162
	v_mov_b32_e32 v171, v163
	v_mov_b32_e32 v172, v164
	v_mov_b32_e32 v173, v165
	v_mov_b32_e32 v174, v166
	v_mov_b32_e32 v175, v167
	s_nop 1
	v_permlane32_swap_b32_e32 v160, v168
	v_permlane32_swap_b32_e32 v161, v169
	v_permlane32_swap_b32_e32 v162, v170
	v_permlane32_swap_b32_e32 v163, v171
	v_permlane32_swap_b32_e32 v164, v172
	v_permlane32_swap_b32_e32 v165, v173
	v_permlane32_swap_b32_e32 v166, v174
	v_permlane32_swap_b32_e32 v167, v175
	s_nop 1
	v_add_f32_e32 v160, v160, v168
	v_add_f32_e32 v161, v161, v169
	v_add_f32_e32 v162, v162, v170
	v_add_f32_e32 v163, v163, v171
	v_add_f32_e32 v164, v164, v172
	v_add_f32_e32 v165, v165, v173
	v_add_f32_e32 v166, v166, v174
	v_add_f32_e32 v167, v167, v175
	v_mov_b32_e32 v168, v160
	v_mov_b32_e32 v169, v161
	v_mov_b32_e32 v170, v162
	v_mov_b32_e32 v171, v163
	v_mov_b32_e32 v172, v164
	v_mov_b32_e32 v173, v165
	v_mov_b32_e32 v174, v166
	v_mov_b32_e32 v175, v167
	s_nop 1
	v_permlane16_swap_b32_e32 v160, v168
	v_permlane16_swap_b32_e32 v161, v169
	v_permlane16_swap_b32_e32 v162, v170
	v_permlane16_swap_b32_e32 v163, v171
	v_permlane16_swap_b32_e32 v164, v172
	v_permlane16_swap_b32_e32 v165, v173
	v_permlane16_swap_b32_e32 v166, v174
	v_permlane16_swap_b32_e32 v167, v175
	s_nop 1
	v_add_f32_e32 v160, v160, v168
	v_add_f32_e32 v161, v161, v169
	v_add_f32_e32 v162, v162, v170
	v_add_f32_e32 v163, v163, v171
	v_add_f32_e32 v164, v164, v172
	v_add_f32_e32 v165, v165, v173
	v_add_f32_e32 v166, v166, v174
	v_add_f32_e32 v167, v167, v175
	v_mov_b32_e32 v178, 0x358637bd
	v_mov_b32_e32 v179, 0x260
	v_fmamk_f32 v160, v160, 0x3a000000, v178
	v_mul_f32_e32 v169, 0x4f800000, v160
	v_cmp_gt_f32_e32 vcc, 0xf800000, v160
	s_nop 1
	v_cndmask_b32_e32 v168, v160, v169, vcc
	v_sqrt_f32_e32 v169, v168
	s_nop 0
	v_add_u32_e32 v170, -1, v169
	v_fma_f32 v171, -v170, v169, v168
	v_cmp_ge_f32_e64 s[18:19], 0, v171
	v_add_u32_e32 v171, 1, v169
	s_nop 0
	v_cndmask_b32_e64 v170, v169, v170, s[18:19]
	v_fma_f32 v169, -v171, v169, v168
	v_cmp_lt_f32_e64 s[18:19], 0, v169
	s_nop 1
	v_cndmask_b32_e64 v169, v170, v171, s[18:19]
	v_mul_f32_e32 v170, 0x37800000, v169
	v_cndmask_b32_e32 v169, v169, v170, vcc
	v_cmp_class_f32_e32 vcc, v168, v179
	s_nop 1
	v_cndmask_b32_e32 v168, v169, v168, vcc
	v_div_scale_f32 v169, s[18:19], v168, v168, 1.0
	v_rcp_f32_e32 v170, v169
	s_nop 1
	v_fma_f32 v171, -v169, v170, 1.0
	v_fmac_f32_e32 v170, v171, v170
	v_div_scale_f32 v171, vcc, 1.0, v168, 1.0
	v_mul_f32_e32 v172, v171, v170
	v_fma_f32 v173, -v169, v172, v171
	v_fmac_f32_e32 v172, v173, v170
	v_fma_f32 v169, -v169, v172, v171
	s_nop 0
	v_div_fmas_f32 v169, v169, v170, v172
	v_div_fixup_f32 v180, v169, v168, 1.0
	v_fmamk_f32 v161, v161, 0x3a000000, v178
	v_mul_f32_e32 v169, 0x4f800000, v161
	v_cmp_gt_f32_e32 vcc, 0xf800000, v161
	s_nop 1
	v_cndmask_b32_e32 v168, v161, v169, vcc
	v_sqrt_f32_e32 v169, v168
	s_nop 0
	v_add_u32_e32 v170, -1, v169
	v_fma_f32 v171, -v170, v169, v168
	v_cmp_ge_f32_e64 s[18:19], 0, v171
	v_add_u32_e32 v171, 1, v169
	s_nop 0
	v_cndmask_b32_e64 v170, v169, v170, s[18:19]
	v_fma_f32 v169, -v171, v169, v168
	v_cmp_lt_f32_e64 s[18:19], 0, v169
	s_nop 1
	v_cndmask_b32_e64 v169, v170, v171, s[18:19]
	v_mul_f32_e32 v170, 0x37800000, v169
	v_cndmask_b32_e32 v169, v169, v170, vcc
	v_cmp_class_f32_e32 vcc, v168, v179
	s_nop 1
	v_cndmask_b32_e32 v168, v169, v168, vcc
	v_div_scale_f32 v169, s[18:19], v168, v168, 1.0
	v_rcp_f32_e32 v170, v169
	s_nop 1
	v_fma_f32 v171, -v169, v170, 1.0
	v_fmac_f32_e32 v170, v171, v170
	v_div_scale_f32 v171, vcc, 1.0, v168, 1.0
	v_mul_f32_e32 v172, v171, v170
	v_fma_f32 v173, -v169, v172, v171
	v_fmac_f32_e32 v172, v173, v170
	v_fma_f32 v169, -v169, v172, v171
	s_nop 0
	v_div_fmas_f32 v169, v169, v170, v172
	v_div_fixup_f32 v182, v169, v168, 1.0
	v_fmamk_f32 v162, v162, 0x3a000000, v178
	v_mul_f32_e32 v169, 0x4f800000, v162
	v_cmp_gt_f32_e32 vcc, 0xf800000, v162
	s_nop 1
	v_cndmask_b32_e32 v168, v162, v169, vcc
	v_sqrt_f32_e32 v169, v168
	s_nop 0
	v_add_u32_e32 v170, -1, v169
	v_fma_f32 v171, -v170, v169, v168
	v_cmp_ge_f32_e64 s[18:19], 0, v171
	v_add_u32_e32 v171, 1, v169
	s_nop 0
	v_cndmask_b32_e64 v170, v169, v170, s[18:19]
	v_fma_f32 v169, -v171, v169, v168
	v_cmp_lt_f32_e64 s[18:19], 0, v169
	s_nop 1
	v_cndmask_b32_e64 v169, v170, v171, s[18:19]
	v_mul_f32_e32 v170, 0x37800000, v169
	v_cndmask_b32_e32 v169, v169, v170, vcc
	v_cmp_class_f32_e32 vcc, v168, v179
	s_nop 1
	v_cndmask_b32_e32 v168, v169, v168, vcc
	v_div_scale_f32 v169, s[18:19], v168, v168, 1.0
	v_rcp_f32_e32 v170, v169
	s_nop 1
	v_fma_f32 v171, -v169, v170, 1.0
	v_fmac_f32_e32 v170, v171, v170
	v_div_scale_f32 v171, vcc, 1.0, v168, 1.0
	v_mul_f32_e32 v172, v171, v170
	v_fma_f32 v173, -v169, v172, v171
	v_fmac_f32_e32 v172, v173, v170
	v_fma_f32 v169, -v169, v172, v171
	s_nop 0
	v_div_fmas_f32 v169, v169, v170, v172
	v_div_fixup_f32 v184, v169, v168, 1.0
	v_fmamk_f32 v163, v163, 0x3a000000, v178
	v_mul_f32_e32 v169, 0x4f800000, v163
	v_cmp_gt_f32_e32 vcc, 0xf800000, v163
	s_nop 1
	v_cndmask_b32_e32 v168, v163, v169, vcc
	v_sqrt_f32_e32 v169, v168
	s_nop 0
	v_add_u32_e32 v170, -1, v169
	v_fma_f32 v171, -v170, v169, v168
	v_cmp_ge_f32_e64 s[18:19], 0, v171
	v_add_u32_e32 v171, 1, v169
	s_nop 0
	v_cndmask_b32_e64 v170, v169, v170, s[18:19]
	v_fma_f32 v169, -v171, v169, v168
	v_cmp_lt_f32_e64 s[18:19], 0, v169
	s_nop 1
	v_cndmask_b32_e64 v169, v170, v171, s[18:19]
	v_mul_f32_e32 v170, 0x37800000, v169
	v_cndmask_b32_e32 v169, v169, v170, vcc
	v_cmp_class_f32_e32 vcc, v168, v179
	s_nop 1
	v_cndmask_b32_e32 v168, v169, v168, vcc
	v_div_scale_f32 v169, s[18:19], v168, v168, 1.0
	v_rcp_f32_e32 v170, v169
	s_nop 1
	v_fma_f32 v171, -v169, v170, 1.0
	v_fmac_f32_e32 v170, v171, v170
	v_div_scale_f32 v171, vcc, 1.0, v168, 1.0
	v_mul_f32_e32 v172, v171, v170
	v_fma_f32 v173, -v169, v172, v171
	v_fmac_f32_e32 v172, v173, v170
	v_fma_f32 v169, -v169, v172, v171
	s_nop 0
	v_div_fmas_f32 v169, v169, v170, v172
	v_div_fixup_f32 v186, v169, v168, 1.0
	v_fmamk_f32 v164, v164, 0x3a000000, v178
	v_mul_f32_e32 v169, 0x4f800000, v164
	v_cmp_gt_f32_e32 vcc, 0xf800000, v164
	s_nop 1
	v_cndmask_b32_e32 v168, v164, v169, vcc
	v_sqrt_f32_e32 v169, v168
	s_nop 0
	v_add_u32_e32 v170, -1, v169
	v_fma_f32 v171, -v170, v169, v168
	v_cmp_ge_f32_e64 s[18:19], 0, v171
	v_add_u32_e32 v171, 1, v169
	s_nop 0
	v_cndmask_b32_e64 v170, v169, v170, s[18:19]
	v_fma_f32 v169, -v171, v169, v168
	v_cmp_lt_f32_e64 s[18:19], 0, v169
	s_nop 1
	v_cndmask_b32_e64 v169, v170, v171, s[18:19]
	v_mul_f32_e32 v170, 0x37800000, v169
	v_cndmask_b32_e32 v169, v169, v170, vcc
	v_cmp_class_f32_e32 vcc, v168, v179
	s_nop 1
	v_cndmask_b32_e32 v168, v169, v168, vcc
	v_div_scale_f32 v169, s[18:19], v168, v168, 1.0
	v_rcp_f32_e32 v170, v169
	s_nop 1
	v_fma_f32 v171, -v169, v170, 1.0
	v_fmac_f32_e32 v170, v171, v170
	v_div_scale_f32 v171, vcc, 1.0, v168, 1.0
	v_mul_f32_e32 v172, v171, v170
	v_fma_f32 v173, -v169, v172, v171
	v_fmac_f32_e32 v172, v173, v170
	v_fma_f32 v169, -v169, v172, v171
	s_nop 0
	v_div_fmas_f32 v169, v169, v170, v172
	v_div_fixup_f32 v188, v169, v168, 1.0
	v_fmamk_f32 v165, v165, 0x3a000000, v178
	v_mul_f32_e32 v169, 0x4f800000, v165
	v_cmp_gt_f32_e32 vcc, 0xf800000, v165
	s_nop 1
	v_cndmask_b32_e32 v168, v165, v169, vcc
	v_sqrt_f32_e32 v169, v168
	s_nop 0
	v_add_u32_e32 v170, -1, v169
	v_fma_f32 v171, -v170, v169, v168
	v_cmp_ge_f32_e64 s[18:19], 0, v171
	v_add_u32_e32 v171, 1, v169
	s_nop 0
	v_cndmask_b32_e64 v170, v169, v170, s[18:19]
	v_fma_f32 v169, -v171, v169, v168
	v_cmp_lt_f32_e64 s[18:19], 0, v169
	s_nop 1
	v_cndmask_b32_e64 v169, v170, v171, s[18:19]
	v_mul_f32_e32 v170, 0x37800000, v169
	v_cndmask_b32_e32 v169, v169, v170, vcc
	v_cmp_class_f32_e32 vcc, v168, v179
	s_nop 1
	v_cndmask_b32_e32 v168, v169, v168, vcc
	v_div_scale_f32 v169, s[18:19], v168, v168, 1.0
	v_rcp_f32_e32 v170, v169
	s_nop 1
	v_fma_f32 v171, -v169, v170, 1.0
	v_fmac_f32_e32 v170, v171, v170
	v_div_scale_f32 v171, vcc, 1.0, v168, 1.0
	v_mul_f32_e32 v172, v171, v170
	v_fma_f32 v173, -v169, v172, v171
	v_fmac_f32_e32 v172, v173, v170
	v_fma_f32 v169, -v169, v172, v171
	s_nop 0
	v_div_fmas_f32 v169, v169, v170, v172
	v_div_fixup_f32 v190, v169, v168, 1.0
	v_fmamk_f32 v166, v166, 0x3a000000, v178
	v_mul_f32_e32 v169, 0x4f800000, v166
	v_cmp_gt_f32_e32 vcc, 0xf800000, v166
	s_nop 1
	v_cndmask_b32_e32 v168, v166, v169, vcc
	v_sqrt_f32_e32 v169, v168
	s_nop 0
	v_add_u32_e32 v170, -1, v169
	v_fma_f32 v171, -v170, v169, v168
	v_cmp_ge_f32_e64 s[18:19], 0, v171
	v_add_u32_e32 v171, 1, v169
	s_nop 0
	v_cndmask_b32_e64 v170, v169, v170, s[18:19]
	v_fma_f32 v169, -v171, v169, v168
	v_cmp_lt_f32_e64 s[18:19], 0, v169
	s_nop 1
	v_cndmask_b32_e64 v169, v170, v171, s[18:19]
	v_mul_f32_e32 v170, 0x37800000, v169
	v_cndmask_b32_e32 v169, v169, v170, vcc
	v_cmp_class_f32_e32 vcc, v168, v179
	s_nop 1
	v_cndmask_b32_e32 v168, v169, v168, vcc
	v_div_scale_f32 v169, s[18:19], v168, v168, 1.0
	v_rcp_f32_e32 v170, v169
	s_nop 1
	v_fma_f32 v171, -v169, v170, 1.0
	v_fmac_f32_e32 v170, v171, v170
	v_div_scale_f32 v171, vcc, 1.0, v168, 1.0
	v_mul_f32_e32 v172, v171, v170
	v_fma_f32 v173, -v169, v172, v171
	v_fmac_f32_e32 v172, v173, v170
	v_fma_f32 v169, -v169, v172, v171
	s_nop 0
	v_div_fmas_f32 v169, v169, v170, v172
	v_div_fixup_f32 v192, v169, v168, 1.0
	v_fmamk_f32 v167, v167, 0x3a000000, v178
	v_mul_f32_e32 v169, 0x4f800000, v167
	v_cmp_gt_f32_e32 vcc, 0xf800000, v167
	s_nop 1
	v_cndmask_b32_e32 v168, v167, v169, vcc
	v_sqrt_f32_e32 v169, v168
	s_nop 0
	v_add_u32_e32 v170, -1, v169
	v_fma_f32 v171, -v170, v169, v168
	v_cmp_ge_f32_e64 s[18:19], 0, v171
	v_add_u32_e32 v171, 1, v169
	s_nop 0
	v_cndmask_b32_e64 v170, v169, v170, s[18:19]
	v_fma_f32 v169, -v171, v169, v168
	v_cmp_lt_f32_e64 s[18:19], 0, v169
	s_nop 1
	v_cndmask_b32_e64 v169, v170, v171, s[18:19]
	v_mul_f32_e32 v170, 0x37800000, v169
	v_cndmask_b32_e32 v169, v169, v170, vcc
	v_cmp_class_f32_e32 vcc, v168, v179
	s_nop 1
	v_cndmask_b32_e32 v168, v169, v168, vcc
	v_div_scale_f32 v169, s[18:19], v168, v168, 1.0
	v_rcp_f32_e32 v170, v169
	s_nop 1
	v_fma_f32 v171, -v169, v170, 1.0
	v_fmac_f32_e32 v170, v171, v170
	v_div_scale_f32 v171, vcc, 1.0, v168, 1.0
	v_mul_f32_e32 v172, v171, v170
	v_fma_f32 v173, -v169, v172, v171
	v_fmac_f32_e32 v172, v173, v170
	v_fma_f32 v169, -v169, v172, v171
	s_nop 0
	v_div_fmas_f32 v169, v169, v170, v172
	v_div_fixup_f32 v194, v169, v168, 1.0
	v_readlane_b32 s100, v253, 3
	v_readlane_b32 s101, v253, 4
	s_add_u32 s100, s100, 0
	s_addc_u32 s101, s101, 0
	s_mul_hi_i32 s18, s95, 0x38e38e39
	s_lshr_b32 s19, s18, 31
	s_ashr_i32 s18, s18, 1
	s_add_i32 s18, s18, s19
	s_add_i32 s18, s18, 1
	s_lshl_b32 s18, s18, 8
	v_subrev_u32_e32 v152, s18, v152
	s_waitcnt vmcnt(0)
	v_add_u32_e32 v154, 0, v152
	v_lshl_add_u32 v154, v154, 13, v153
	v_pk_mul_f32 v[124:125], v[124:125], v[180:181] op_sel_hi:[1,0]
	v_pk_mul_f32 v[126:127], v[126:127], v[180:181] op_sel_hi:[1,0]
	v_pk_mul_f32 v[124:125], v[124:125], v[132:133]
	v_pk_mul_f32 v[126:127], v[126:127], v[134:135]
	v_pk_mul_f32 v[120:121], v[120:121], v[180:181] op_sel_hi:[1,0]
	v_pk_mul_f32 v[122:123], v[122:123], v[180:181] op_sel_hi:[1,0]
	v_pk_mul_f32 v[120:121], v[120:121], v[136:137]
	v_pk_mul_f32 v[122:123], v[122:123], v[138:139]
	v_pk_mul_f32 v[104:105], v[104:105], v[180:181] op_sel_hi:[1,0]
	v_pk_mul_f32 v[106:107], v[106:107], v[180:181] op_sel_hi:[1,0]
	v_pk_mul_f32 v[104:105], v[104:105], v[140:141]
	v_pk_mul_f32 v[106:107], v[106:107], v[142:143]
	v_pk_mul_f32 v[96:97], v[96:97], v[180:181] op_sel_hi:[1,0]
	v_pk_mul_f32 v[98:99], v[98:99], v[180:181] op_sel_hi:[1,0]
	v_pk_mul_f32 v[96:97], v[96:97], v[244:245]
	v_pk_mul_f32 v[98:99], v[98:99], v[246:247]
	global_store_dwordx4 v154, v[124:127], s[100:101] offset:0 sc1
	global_store_dwordx4 v154, v[120:123], s[100:101] offset:64 sc1
	global_store_dwordx4 v154, v[104:107], s[100:101] offset:512 sc1
	global_store_dwordx4 v154, v[96:99], s[100:101] offset:576 sc1
	v_add_u32_e32 v154, 16, v152
	v_lshl_add_u32 v154, v154, 13, v153
	v_pk_mul_f32 v[116:117], v[116:117], v[182:183] op_sel_hi:[1,0]
	v_pk_mul_f32 v[118:119], v[118:119], v[182:183] op_sel_hi:[1,0]
	v_pk_mul_f32 v[116:117], v[116:117], v[132:133]
	v_pk_mul_f32 v[118:119], v[118:119], v[134:135]
	v_pk_mul_f32 v[112:113], v[112:113], v[182:183] op_sel_hi:[1,0]
	v_pk_mul_f32 v[114:115], v[114:115], v[182:183] op_sel_hi:[1,0]
	v_pk_mul_f32 v[112:113], v[112:113], v[136:137]
	v_pk_mul_f32 v[114:115], v[114:115], v[138:139]
	v_pk_mul_f32 v[88:89], v[88:89], v[182:183] op_sel_hi:[1,0]
	v_pk_mul_f32 v[90:91], v[90:91], v[182:183] op_sel_hi:[1,0]
	v_pk_mul_f32 v[88:89], v[88:89], v[140:141]
	v_pk_mul_f32 v[90:91], v[90:91], v[142:143]
	v_pk_mul_f32 v[84:85], v[84:85], v[182:183] op_sel_hi:[1,0]
	v_pk_mul_f32 v[86:87], v[86:87], v[182:183] op_sel_hi:[1,0]
	v_pk_mul_f32 v[84:85], v[84:85], v[244:245]
	v_pk_mul_f32 v[86:87], v[86:87], v[246:247]
	global_store_dwordx4 v154, v[116:119], s[100:101] offset:0 sc1
	global_store_dwordx4 v154, v[112:115], s[100:101] offset:64 sc1
	global_store_dwordx4 v154, v[88:91], s[100:101] offset:512 sc1
	global_store_dwordx4 v154, v[84:87], s[100:101] offset:576 sc1
	v_add_u32_e32 v154, 32, v152
	v_lshl_add_u32 v154, v154, 13, v153
	v_pk_mul_f32 v[108:109], v[108:109], v[184:185] op_sel_hi:[1,0]
	v_pk_mul_f32 v[110:111], v[110:111], v[184:185] op_sel_hi:[1,0]
	v_pk_mul_f32 v[108:109], v[108:109], v[132:133]
	v_pk_mul_f32 v[110:111], v[110:111], v[134:135]
	v_pk_mul_f32 v[100:101], v[100:101], v[184:185] op_sel_hi:[1,0]
	v_pk_mul_f32 v[102:103], v[102:103], v[184:185] op_sel_hi:[1,0]
	v_pk_mul_f32 v[100:101], v[100:101], v[136:137]
	v_pk_mul_f32 v[102:103], v[102:103], v[138:139]
	v_pk_mul_f32 v[80:81], v[80:81], v[184:185] op_sel_hi:[1,0]
	v_pk_mul_f32 v[82:83], v[82:83], v[184:185] op_sel_hi:[1,0]
	v_pk_mul_f32 v[80:81], v[80:81], v[140:141]
	v_pk_mul_f32 v[82:83], v[82:83], v[142:143]
	v_pk_mul_f32 v[76:77], v[76:77], v[184:185] op_sel_hi:[1,0]
	v_pk_mul_f32 v[78:79], v[78:79], v[184:185] op_sel_hi:[1,0]
	v_pk_mul_f32 v[76:77], v[76:77], v[244:245]
	v_pk_mul_f32 v[78:79], v[78:79], v[246:247]
	global_store_dwordx4 v154, v[108:111], s[100:101] offset:0 sc1
	global_store_dwordx4 v154, v[100:103], s[100:101] offset:64 sc1
	global_store_dwordx4 v154, v[80:83], s[100:101] offset:512 sc1
	global_store_dwordx4 v154, v[76:79], s[100:101] offset:576 sc1
	v_add_u32_e32 v154, 48, v152
	v_lshl_add_u32 v154, v154, 13, v153
	v_pk_mul_f32 v[92:93], v[92:93], v[186:187] op_sel_hi:[1,0]
	v_pk_mul_f32 v[94:95], v[94:95], v[186:187] op_sel_hi:[1,0]
	v_pk_mul_f32 v[92:93], v[92:93], v[132:133]
	v_pk_mul_f32 v[94:95], v[94:95], v[134:135]
	v_pk_mul_f32 v[72:73], v[72:73], v[186:187] op_sel_hi:[1,0]
	v_pk_mul_f32 v[74:75], v[74:75], v[186:187] op_sel_hi:[1,0]
	v_pk_mul_f32 v[72:73], v[72:73], v[136:137]
	v_pk_mul_f32 v[74:75], v[74:75], v[138:139]
	v_pk_mul_f32 v[68:69], v[68:69], v[186:187] op_sel_hi:[1,0]
	v_pk_mul_f32 v[70:71], v[70:71], v[186:187] op_sel_hi:[1,0]
	v_pk_mul_f32 v[68:69], v[68:69], v[140:141]
	v_pk_mul_f32 v[70:71], v[70:71], v[142:143]
	v_pk_mul_f32 v[64:65], v[64:65], v[186:187] op_sel_hi:[1,0]
	v_pk_mul_f32 v[66:67], v[66:67], v[186:187] op_sel_hi:[1,0]
	v_pk_mul_f32 v[64:65], v[64:65], v[244:245]
	v_pk_mul_f32 v[66:67], v[66:67], v[246:247]
	global_store_dwordx4 v154, v[92:95], s[100:101] offset:0 sc1
	global_store_dwordx4 v154, v[72:75], s[100:101] offset:64 sc1
	global_store_dwordx4 v154, v[68:71], s[100:101] offset:512 sc1
	global_store_dwordx4 v154, v[64:67], s[100:101] offset:576 sc1
	v_add_u32_e32 v154, 128, v152
	v_lshl_add_u32 v154, v154, 13, v153
	v_pk_mul_f32 v[60:61], v[60:61], v[188:189] op_sel_hi:[1,0]
	v_pk_mul_f32 v[62:63], v[62:63], v[188:189] op_sel_hi:[1,0]
	v_pk_mul_f32 v[60:61], v[60:61], v[132:133]
	v_pk_mul_f32 v[62:63], v[62:63], v[134:135]
	v_pk_mul_f32 v[56:57], v[56:57], v[188:189] op_sel_hi:[1,0]
	v_pk_mul_f32 v[58:59], v[58:59], v[188:189] op_sel_hi:[1,0]
	v_pk_mul_f32 v[56:57], v[56:57], v[136:137]
	v_pk_mul_f32 v[58:59], v[58:59], v[138:139]
	v_pk_mul_f32 v[40:41], v[40:41], v[188:189] op_sel_hi:[1,0]
	v_pk_mul_f32 v[42:43], v[42:43], v[188:189] op_sel_hi:[1,0]
	v_pk_mul_f32 v[40:41], v[40:41], v[140:141]
	v_pk_mul_f32 v[42:43], v[42:43], v[142:143]
	v_pk_mul_f32 v[36:37], v[36:37], v[188:189] op_sel_hi:[1,0]
	v_pk_mul_f32 v[38:39], v[38:39], v[188:189] op_sel_hi:[1,0]
	v_pk_mul_f32 v[36:37], v[36:37], v[244:245]
	v_pk_mul_f32 v[38:39], v[38:39], v[246:247]
	global_store_dwordx4 v154, v[60:63], s[100:101] offset:0 sc1
	global_store_dwordx4 v154, v[56:59], s[100:101] offset:64 sc1
	global_store_dwordx4 v154, v[40:43], s[100:101] offset:512 sc1
	global_store_dwordx4 v154, v[36:39], s[100:101] offset:576 sc1
	v_add_u32_e32 v154, 144, v152
	v_lshl_add_u32 v154, v154, 13, v153
	v_pk_mul_f32 v[52:53], v[52:53], v[190:191] op_sel_hi:[1,0]
	v_pk_mul_f32 v[54:55], v[54:55], v[190:191] op_sel_hi:[1,0]
	v_pk_mul_f32 v[52:53], v[52:53], v[132:133]
	v_pk_mul_f32 v[54:55], v[54:55], v[134:135]
	v_pk_mul_f32 v[48:49], v[48:49], v[190:191] op_sel_hi:[1,0]
	v_pk_mul_f32 v[50:51], v[50:51], v[190:191] op_sel_hi:[1,0]
	v_pk_mul_f32 v[48:49], v[48:49], v[136:137]
	v_pk_mul_f32 v[50:51], v[50:51], v[138:139]
	v_pk_mul_f32 v[28:29], v[28:29], v[190:191] op_sel_hi:[1,0]
	v_pk_mul_f32 v[30:31], v[30:31], v[190:191] op_sel_hi:[1,0]
	v_pk_mul_f32 v[28:29], v[28:29], v[140:141]
	v_pk_mul_f32 v[30:31], v[30:31], v[142:143]
	v_pk_mul_f32 v[24:25], v[24:25], v[190:191] op_sel_hi:[1,0]
	v_pk_mul_f32 v[26:27], v[26:27], v[190:191] op_sel_hi:[1,0]
	v_pk_mul_f32 v[24:25], v[24:25], v[244:245]
	v_pk_mul_f32 v[26:27], v[26:27], v[246:247]
	global_store_dwordx4 v154, v[52:55], s[100:101] offset:0 sc1
	global_store_dwordx4 v154, v[48:51], s[100:101] offset:64 sc1
	global_store_dwordx4 v154, v[28:31], s[100:101] offset:512 sc1
	global_store_dwordx4 v154, v[24:27], s[100:101] offset:576 sc1
	v_add_u32_e32 v154, 160, v152
	v_lshl_add_u32 v154, v154, 13, v153
	v_pk_mul_f32 v[44:45], v[44:45], v[192:193] op_sel_hi:[1,0]
	v_pk_mul_f32 v[46:47], v[46:47], v[192:193] op_sel_hi:[1,0]
	v_pk_mul_f32 v[44:45], v[44:45], v[132:133]
	v_pk_mul_f32 v[46:47], v[46:47], v[134:135]
	v_pk_mul_f32 v[32:33], v[32:33], v[192:193] op_sel_hi:[1,0]
	v_pk_mul_f32 v[34:35], v[34:35], v[192:193] op_sel_hi:[1,0]
	v_pk_mul_f32 v[32:33], v[32:33], v[136:137]
	v_pk_mul_f32 v[34:35], v[34:35], v[138:139]
	v_pk_mul_f32 v[20:21], v[20:21], v[192:193] op_sel_hi:[1,0]
	v_pk_mul_f32 v[22:23], v[22:23], v[192:193] op_sel_hi:[1,0]
	v_pk_mul_f32 v[20:21], v[20:21], v[140:141]
	v_pk_mul_f32 v[22:23], v[22:23], v[142:143]
	v_pk_mul_f32 v[12:13], v[12:13], v[192:193] op_sel_hi:[1,0]
	v_pk_mul_f32 v[14:15], v[14:15], v[192:193] op_sel_hi:[1,0]
	v_pk_mul_f32 v[12:13], v[12:13], v[244:245]
	v_pk_mul_f32 v[14:15], v[14:15], v[246:247]
	global_store_dwordx4 v154, v[44:47], s[100:101] offset:0 sc1
	global_store_dwordx4 v154, v[32:35], s[100:101] offset:64 sc1
	global_store_dwordx4 v154, v[20:23], s[100:101] offset:512 sc1
	global_store_dwordx4 v154, v[12:15], s[100:101] offset:576 sc1
	v_add_u32_e32 v154, 176, v152
	v_lshl_add_u32 v154, v154, 13, v153
	v_pk_mul_f32 v[16:17], v[16:17], v[194:195] op_sel_hi:[1,0]
	v_pk_mul_f32 v[18:19], v[18:19], v[194:195] op_sel_hi:[1,0]
	v_pk_mul_f32 v[16:17], v[16:17], v[132:133]
	v_pk_mul_f32 v[18:19], v[18:19], v[134:135]
	v_pk_mul_f32 v[8:9], v[8:9], v[194:195] op_sel_hi:[1,0]
	v_pk_mul_f32 v[10:11], v[10:11], v[194:195] op_sel_hi:[1,0]
	v_pk_mul_f32 v[8:9], v[8:9], v[136:137]
	v_pk_mul_f32 v[10:11], v[10:11], v[138:139]
	v_pk_mul_f32 v[4:5], v[4:5], v[194:195] op_sel_hi:[1,0]
	v_pk_mul_f32 v[6:7], v[6:7], v[194:195] op_sel_hi:[1,0]
	v_pk_mul_f32 v[4:5], v[4:5], v[140:141]
	v_pk_mul_f32 v[6:7], v[6:7], v[142:143]
	v_pk_mul_f32 v[0:1], v[0:1], v[194:195] op_sel_hi:[1,0]
	v_pk_mul_f32 v[2:3], v[2:3], v[194:195] op_sel_hi:[1,0]
	v_pk_mul_f32 v[0:1], v[0:1], v[244:245]
	v_pk_mul_f32 v[2:3], v[2:3], v[246:247]
	global_store_dwordx4 v154, v[16:19], s[100:101] offset:0 sc1
	global_store_dwordx4 v154, v[8:11], s[100:101] offset:64 sc1
	global_store_dwordx4 v154, v[4:7], s[100:101] offset:512 sc1
	global_store_dwordx4 v154, v[0:3], s[100:101] offset:576 sc1
	s_branch .LBB0_1807
